# v68 + diff-attention combine loop: next step's loads issued ahead of the arithmetic (shadow registers)
# speedup vs baseline: 1.0001x; 1.0001x over previous
.LBB0_655:
	v_readlane_b32 s0, v254, 31
	v_readlane_b32 s1, v254, 32
	v_readlane_b32 s56, v254, 15
	v_readlane_b32 s66, v254, 17
	v_readlane_b32 s68, v254, 19
	s_and_b64 vcc, exec, s[0:1]
	v_readlane_b32 s57, v254, 16
	v_readlane_b32 s67, v254, 18
	v_readlane_b32 s69, v254, 20
	s_movk_i32 s90, 0xff
	s_mov_b32 s91, 0x8000
	s_movk_i32 s94, 0x4000
	s_mov_b32 s95, 0xc000
	v_readlane_b32 s51, v254, 14
	s_mov_b32 s47, 0x9000
	s_movk_i32 s50, 0x1000
	s_movk_i32 s43, 0x3000
	s_movk_i32 s46, 0x6000
	s_cbranch_vccz .LBB0_486
	v_readlane_b32 s0, v254, 7
	s_mov_b32 s6, s72
	s_waitcnt vmcnt(0)
	v_mbcnt_lo_u32_b32 v16, -1, 0
	v_mbcnt_hi_u32_b32 v16, -1, v16
	s_cmp_eq_u32 s6, 0
	v_mov_b32_e32 v0, s0
	ds_read2_b64 v[0:3], v0 offset1:1
	s_cselect_b64 vcc, -1, 0
	s_ashr_i32 s7, s6, 31
	s_lshl_b64 s[0:1], s[6:7], 11
	v_and_b32_e32 v4, 63, v16
	s_waitcnt lgkmcnt(0)
	v_readfirstlane_b32 s4, v0
	v_readfirstlane_b32 s5, v1
	s_add_u32 s0, s4, s0
	s_addc_u32 s1, s5, s1
	v_lshlrev_b32_e32 v160, 2, v4
	v_lshl_add_u64 v[0:1], s[0:1], 0, v[160:161]
	flat_load_dword v4, v[0:1]
	flat_load_dword v5, v[0:1] offset:512
	flat_load_dword v6, v[0:1] offset:256
	flat_load_dword v7, v[0:1] offset:768
	v_xor_b32_e32 v22, 32, v160
	v_xor_b32_e32 v23, 16, v160
	v_xor_b32_e32 v24, 8, v160
	v_xor_b32_e32 v25, 4, v160
	s_mov_b32 s5, 0x3fb8aa3b
	s_mov_b32 s8, 0xc2ce8ed0
	s_mov_b32 s9, 0x42b17218
	v_bfe_u32 v18, v16, 4, 2
	v_mov_b32_e32 v21, 0x3e4ccccd
	s_mov_b32 s4, 9
	s_waitcnt vmcnt(0) lgkmcnt(0)
	v_mul_f32_e32 v6, v6, v7
	v_fmac_f32_e32 v6, v4, v5
	flat_load_dword v4, v[0:1] offset:1024
	flat_load_dword v5, v[0:1] offset:1536
	flat_load_dword v7, v[0:1] offset:1280
	s_nop 0
	flat_load_dword v0, v[0:1] offset:1792
	v_xor_b32_e32 v1, 0x80, v160
	s_waitcnt vmcnt(0) lgkmcnt(0)
	v_mul_f32_e32 v0, v7, v0
	v_fmac_f32_e32 v0, v4, v5
	ds_bpermute_b32 v4, v1, v6
	ds_bpermute_b32 v1, v1, v0
	v_mov_b32_e32 v7, 0x7f800000
	s_waitcnt lgkmcnt(1)
	v_add_f32_e32 v4, v6, v4
	s_waitcnt lgkmcnt(0)
	v_add_f32_e32 v0, v0, v1
	v_xor_b32_e32 v1, 64, v160
	ds_bpermute_b32 v5, v1, v4
	ds_bpermute_b32 v1, v1, v0
	s_waitcnt lgkmcnt(1)
	v_add_f32_e32 v4, v4, v5
	s_waitcnt lgkmcnt(0)
	v_add_f32_e32 v0, v0, v1
	ds_bpermute_b32 v1, v22, v4
	s_waitcnt lgkmcnt(0)
	v_add_f32_e32 v1, v4, v1
	ds_bpermute_b32 v4, v22, v0
	s_waitcnt lgkmcnt(0)
	v_add_f32_e32 v0, v0, v4
	ds_bpermute_b32 v4, v23, v1
	s_waitcnt lgkmcnt(0)
	v_add_f32_e32 v1, v1, v4
	ds_bpermute_b32 v4, v23, v0
	s_waitcnt lgkmcnt(0)
	v_add_f32_e32 v0, v0, v4
	ds_bpermute_b32 v4, v24, v1
	s_waitcnt lgkmcnt(0)
	v_add_f32_e32 v1, v1, v4
	ds_bpermute_b32 v4, v24, v0
	s_waitcnt lgkmcnt(0)
	v_add_f32_e32 v0, v0, v4
	ds_bpermute_b32 v4, v25, v1
	s_waitcnt lgkmcnt(0)
	v_add_f32_e32 v1, v1, v4
	ds_bpermute_b32 v4, v25, v0
	v_cmp_ngt_f32_e64 s[0:1], s8, v1
	s_waitcnt lgkmcnt(0)
	v_add_f32_e32 v0, v0, v4
	v_mul_f32_e32 v4, 0x3fb8aa3b, v1
	v_fma_f32 v5, v1, s5, -v4
	v_rndne_f32_e32 v6, v4
	v_fmac_f32_e32 v5, 0x32a5705f, v1
	v_sub_f32_e32 v4, v4, v6
	v_add_f32_e32 v4, v4, v5
	v_exp_f32_e32 v4, v4
	v_cvt_i32_f32_e32 v5, v6
	v_ldexp_f32 v4, v4, v5
	v_cndmask_b32_e64 v4, 0, v4, s[0:1]
	v_cmp_nlt_f32_e64 s[0:1], s9, v1
	s_nop 1
	v_cndmask_b32_e64 v1, v7, v4, s[0:1]
	v_mul_f32_e32 v4, 0x3fb8aa3b, v0
	v_fma_f32 v5, v0, s5, -v4
	v_rndne_f32_e32 v6, v4
	v_fmac_f32_e32 v5, 0x32a5705f, v0
	v_sub_f32_e32 v4, v4, v6
	v_add_f32_e32 v4, v4, v5
	v_exp_f32_e32 v4, v4
	v_cvt_i32_f32_e32 v5, v6
	v_cmp_ngt_f32_e64 s[0:1], s8, v0
	v_readfirstlane_b32 s5, v2
	v_readfirstlane_b32 s8, v3
	v_ldexp_f32 v4, v4, v5
	v_cndmask_b32_e64 v4, 0, v4, s[0:1]
	v_cmp_nlt_f32_e64 s[0:1], s9, v0
	s_nop 1
	v_cndmask_b32_e64 v0, v7, v4, s[0:1]
	v_sub_f32_e32 v17, v1, v0
	s_lshl_b64 s[0:1], s[6:7], 10
	v_lshlrev_b32_e32 v0, 4, v16
	s_add_u32 s0, s5, s0
	v_and_b32_e32 v20, 0xf0, v0
	s_addc_u32 s1, s8, s1
	v_lshlrev_b32_e32 v160, 2, v20
	v_lshl_add_u64 v[12:13], s[0:1], 0, v[160:161]
	flat_load_dwordx4 v[0:3], v[12:13]
	flat_load_dwordx4 v[4:7], v[12:13] offset:16
	flat_load_dwordx4 v[8:11], v[12:13] offset:32
	s_nop 0
	flat_load_dwordx4 v[12:15], v[12:13] offset:48
	v_readlane_b32 s0, v253, 53
	v_readlane_b32 s8, v253, 55
	v_readlane_b32 s10, v253, 57
	v_add_u32_e32 v19, s0, v16
	v_mov_b32_e32 v16, 0x3eb60549
	v_cndmask_b32_e32 v21, v16, v21, vcc
	v_add_f32_e32 v16, v21, v17
	v_ashrrev_i32_e32 v17, 1, v19
	v_and_b32_e32 v26, 0xffffffe0, v17
	v_mov_b32_e32 v19, v161
	v_ashrrev_i32_e32 v27, 31, v26
	v_lshl_add_u64 v[18:19], s[20:21], 0, v[18:19]
	v_lshl_add_u64 v[28:29], v[18:19], 0, v[26:27]
	v_lshlrev_b32_e32 v18, 1, v20
	v_sub_f32_e32 v26, 1.0, v21
	v_lshl_or_b32 v160, s27, 9, v18
	v_lshlrev_b64 v[18:19], 13, v[28:29]
	v_readlane_b32 s11, v253, 58
	v_lshlrev_b64 v[20:21], 11, v[28:29]
	v_mov_b32_e32 v17, v16
	v_lshl_add_u64 v[18:19], s[10:11], 0, v[18:19]
	v_lshl_add_u64 v[20:21], s[10:11], 0, v[20:21]
	s_mov_b32 s5, 0x800000
	s_mov_b64 s[6:7], 0x2000
	v_readlane_b32 s9, v253, 56
	v_lshl_add_u64 v[36:37], v[20:21], 0, v[160:161]
	s_mov_b64 s[0:1], 0x5df00000
	v_add_co_u32_e32 v28, vcc, 0x5df00000, v36
	v_lshl_add_u64 v[32:33], v[36:37], 0, s[0:1]
	s_mov_b64 s[0:1], 0x62700000
	v_addc_co_u32_e32 v29, vcc, 0, v37, vcc
	v_lshl_add_u64 v[40:41], v[36:37], 0, s[0:1]
	v_add_co_u32_e32 v36, vcc, 0x62700000, v36
	v_lshl_add_u64 v[52:53], v[18:19], 0, v[160:161]
	s_nop 0
	v_addc_co_u32_e32 v37, vcc, 0, v37, vcc
	s_mov_b64 s[0:1], 0x4bf01800
	v_add_co_u32_e32 v44, vcc, 0x4bf01000, v52
	v_lshl_add_u64 v[48:49], v[52:53], 0, s[0:1]
	s_nop 0
	v_addc_co_u32_e32 v45, vcc, 0, v53, vcc
	global_load_dwordx4 v[28:31], v[28:29], off
	s_nop 0
	global_load_dwordx4 v[32:35], v[32:33], off offset:16
	s_nop 0
	global_load_dwordx4 v[36:39], v[36:37], off
	s_nop 0
	global_load_dwordx4 v[40:43], v[40:41], off offset:16
	s_nop 0
	global_load_dwordx4 v[44:47], v[44:45], off offset:2048
	s_nop 0
	global_load_dwordx4 v[48:51], v[48:49], off offset:16
	s_add_i32 s4, s4, -1
	s_mov_b64 s[0:1], 0x8000
	v_lshl_add_u64 v[18:19], v[18:19], 0, s[0:1]
	v_lshl_add_u64 v[20:21], v[20:21], 0, s[6:7]
	s_cmp_lg_u32 s4, 0
.LBB0_657:
	s_waitcnt vmcnt(0)
	v_mov_b32_e32 v128, v28
	v_mov_b32_e32 v129, v29
	v_mov_b32_e32 v130, v30
	v_mov_b32_e32 v131, v31
	v_mov_b32_e32 v132, v32
	v_mov_b32_e32 v133, v33
	v_mov_b32_e32 v134, v34
	v_mov_b32_e32 v135, v35
	v_mov_b32_e32 v136, v36
	v_mov_b32_e32 v137, v37
	v_mov_b32_e32 v138, v38
	v_mov_b32_e32 v139, v39
	v_mov_b32_e32 v140, v40
	v_mov_b32_e32 v141, v41
	v_mov_b32_e32 v142, v42
	v_mov_b32_e32 v143, v43
	v_mov_b32_e32 v144, v44
	v_mov_b32_e32 v145, v45
	v_mov_b32_e32 v146, v46
	v_mov_b32_e32 v147, v47
	v_mov_b32_e32 v148, v48
	v_mov_b32_e32 v149, v49
	v_mov_b32_e32 v150, v50
	v_mov_b32_e32 v151, v51
	v_mov_b32_e32 v152, v52
	v_mov_b32_e32 v153, v53
	v_lshl_add_u64 v[36:37], v[20:21], 0, v[160:161]
	s_mov_b64 s[0:1], 0x5df00000
	v_add_co_u32_e32 v28, vcc, 0x5df00000, v36
	v_lshl_add_u64 v[32:33], v[36:37], 0, s[0:1]
	s_mov_b64 s[0:1], 0x62700000
	v_addc_co_u32_e32 v29, vcc, 0, v37, vcc
	v_lshl_add_u64 v[40:41], v[36:37], 0, s[0:1]
	v_add_co_u32_e32 v36, vcc, 0x62700000, v36
	v_lshl_add_u64 v[52:53], v[18:19], 0, v[160:161]
	s_nop 0
	v_addc_co_u32_e32 v37, vcc, 0, v37, vcc
	s_mov_b64 s[0:1], 0x4bf01800
	v_add_co_u32_e32 v44, vcc, 0x4bf01000, v52
	v_lshl_add_u64 v[48:49], v[52:53], 0, s[0:1]
	s_nop 0
	v_addc_co_u32_e32 v45, vcc, 0, v53, vcc
	global_load_dwordx4 v[28:31], v[28:29], off
	s_nop 0
	global_load_dwordx4 v[32:35], v[32:33], off offset:16
	s_nop 0
	global_load_dwordx4 v[36:39], v[36:37], off
	s_nop 0
	global_load_dwordx4 v[40:43], v[40:41], off offset:16
	s_nop 0
	global_load_dwordx4 v[44:47], v[44:45], off offset:2048
	s_nop 0
	global_load_dwordx4 v[48:51], v[48:49], off offset:16
	s_add_i32 s4, s4, -1
	s_mov_b64 s[0:1], 0x8000
	v_lshl_add_u64 v[18:19], v[18:19], 0, s[0:1]
	v_lshl_add_u64 v[20:21], v[20:21], 0, s[6:7]
	s_cmp_lg_u32 s4, 0
	v_lshlrev_b32_e32 v58, 16, v130
	v_lshlrev_b32_e32 v66, 16, v134
	v_lshlrev_b32_e32 v68, 16, v142
	v_lshlrev_b32_e32 v76, 16, v150
	v_mul_f32_e32 v27, 0xbfb8aa3b, v76
	v_exp_f32_e32 v27, v27
	v_and_b32_e32 v67, 0xffff0000, v134
	v_and_b32_e32 v69, 0xffff0000, v142
	v_lshlrev_b32_e32 v134, 16, v135
	v_lshlrev_b32_e32 v142, 16, v143
	v_and_b32_e32 v135, 0xffff0000, v135
	v_and_b32_e32 v143, 0xffff0000, v143
	v_pk_fma_f32 v[142:143], v[16:17], v[142:143], v[134:135] neg_lo:[1,0,0] neg_hi:[1,0,0]
	v_pk_fma_f32 v[134:135], v[16:17], v[68:69], v[66:67] neg_lo:[1,0,0] neg_hi:[1,0,0]
	v_mov_b32_e32 v69, v143
	v_mov_b32_e32 v68, v135
	v_and_b32_e32 v77, 0xffff0000, v150
	v_mov_b32_e32 v66, v134
	v_mov_b32_e32 v67, v142
	v_pk_mul_f32 v[68:69], v[68:69], v[68:69]
	v_add_f32_e32 v27, 1.0, v27
	v_pk_fma_f32 v[66:67], v[66:67], v[66:67], v[68:69]
	v_rcp_f32_e32 v68, v27
	v_mul_f32_e32 v27, 0xbfb8aa3b, v77
	v_exp_f32_e32 v27, v27
	v_lshlrev_b32_e32 v74, 16, v148
	v_and_b32_e32 v75, 0xffff0000, v148
	v_lshlrev_b32_e32 v148, 16, v149
	v_add_f32_e32 v27, 1.0, v27
	v_rcp_f32_e32 v69, v27
	v_mul_f32_e32 v27, 0xbfb8aa3b, v148
	v_exp_f32_e32 v27, v27
	v_lshlrev_b32_e32 v62, 16, v132
	v_lshlrev_b32_e32 v64, 16, v140
	v_and_b32_e32 v63, 0xffff0000, v132
	v_and_b32_e32 v65, 0xffff0000, v140
	v_lshlrev_b32_e32 v132, 16, v133
	v_lshlrev_b32_e32 v140, 16, v141
	v_and_b32_e32 v133, 0xffff0000, v133
	v_and_b32_e32 v141, 0xffff0000, v141
	v_and_b32_e32 v149, 0xffff0000, v149
	v_add_f32_e32 v27, 1.0, v27
	v_pk_fma_f32 v[140:141], v[16:17], v[140:141], v[132:133] neg_lo:[1,0,0] neg_hi:[1,0,0]
	v_rcp_f32_e32 v132, v27
	v_mul_f32_e32 v27, 0xbfb8aa3b, v149
	v_exp_f32_e32 v27, v27
	v_lshlrev_b32_e32 v72, 16, v146
	v_and_b32_e32 v73, 0xffff0000, v146
	v_lshlrev_b32_e32 v146, 16, v147
	v_add_f32_e32 v27, 1.0, v27
	v_rcp_f32_e32 v133, v27
	v_mul_f32_e32 v27, 0xbfb8aa3b, v74
	v_exp_f32_e32 v27, v27
	v_lshlrev_b32_e32 v60, 16, v138
	v_pk_mul_f32 v[148:149], v[132:133], v[148:149]
	v_pk_fma_f32 v[132:133], v[16:17], v[64:65], v[62:63] neg_lo:[1,0,0] neg_hi:[1,0,0]
	v_mov_b32_e32 v65, v141
	v_mov_b32_e32 v64, v133
	v_mov_b32_e32 v62, v132
	v_mov_b32_e32 v63, v140
	v_pk_mul_f32 v[64:65], v[64:65], v[64:65]
	v_add_f32_e32 v27, 1.0, v27
	v_pk_fma_f32 v[62:63], v[62:63], v[62:63], v[64:65]
	v_rcp_f32_e32 v64, v27
	v_mul_f32_e32 v27, 0xbfb8aa3b, v75
	v_exp_f32_e32 v27, v27
	v_and_b32_e32 v59, 0xffff0000, v130
	v_and_b32_e32 v61, 0xffff0000, v138
	v_lshlrev_b32_e32 v130, 16, v131
	v_add_f32_e32 v27, 1.0, v27
	v_rcp_f32_e32 v65, v27
	v_mul_f32_e32 v27, 0xbfb8aa3b, v146
	v_exp_f32_e32 v27, v27
	v_lshlrev_b32_e32 v138, 16, v139
	v_and_b32_e32 v131, 0xffff0000, v131
	v_and_b32_e32 v139, 0xffff0000, v139
	v_and_b32_e32 v147, 0xffff0000, v147
	v_add_f32_e32 v27, 1.0, v27
	v_pk_fma_f32 v[138:139], v[16:17], v[138:139], v[130:131] neg_lo:[1,0,0] neg_hi:[1,0,0]
	v_rcp_f32_e32 v130, v27
	v_mul_f32_e32 v27, 0xbfb8aa3b, v147
	v_exp_f32_e32 v27, v27
	v_lshlrev_b32_e32 v70, 16, v144
	v_and_b32_e32 v71, 0xffff0000, v144
	v_lshlrev_b32_e32 v144, 16, v145
	v_add_f32_e32 v27, 1.0, v27
	v_rcp_f32_e32 v131, v27
	v_mul_f32_e32 v27, 0xbfb8aa3b, v72
	v_exp_f32_e32 v27, v27
	v_and_b32_e32 v145, 0xffff0000, v145
	v_pk_mul_f32 v[146:147], v[130:131], v[146:147]
	v_pk_fma_f32 v[130:131], v[16:17], v[60:61], v[58:59] neg_lo:[1,0,0] neg_hi:[1,0,0]
	v_mov_b32_e32 v61, v139
	v_mov_b32_e32 v60, v131
	v_mov_b32_e32 v58, v130
	v_mov_b32_e32 v59, v138
	v_pk_mul_f32 v[60:61], v[60:61], v[60:61]
	v_add_f32_e32 v27, 1.0, v27
	v_pk_fma_f32 v[58:59], v[58:59], v[58:59], v[60:61]
	v_rcp_f32_e32 v60, v27
	v_mul_f32_e32 v27, 0xbfb8aa3b, v73
	v_exp_f32_e32 v27, v27
	v_lshlrev_b32_e32 v54, 16, v128
	v_lshlrev_b32_e32 v56, 16, v136
	v_and_b32_e32 v55, 0xffff0000, v128
	v_add_f32_e32 v27, 1.0, v27
	v_rcp_f32_e32 v61, v27
	v_mul_f32_e32 v27, 0xbfb8aa3b, v144
	v_exp_f32_e32 v27, v27
	v_and_b32_e32 v57, 0xffff0000, v136
	v_pk_mul_f32 v[60:61], v[60:61], v[72:73]
	v_lshlrev_b32_e32 v128, 16, v129
	v_add_f32_e32 v27, 1.0, v27
	v_rcp_f32_e32 v72, v27
	v_mul_f32_e32 v27, 0xbfb8aa3b, v145
	v_exp_f32_e32 v27, v27
	v_lshlrev_b32_e32 v136, 16, v137
	v_and_b32_e32 v129, 0xffff0000, v129
	v_and_b32_e32 v137, 0xffff0000, v137
	v_add_f32_e32 v27, 1.0, v27
	v_rcp_f32_e32 v73, v27
	v_mul_f32_e32 v27, 0xbfb8aa3b, v70
	v_exp_f32_e32 v27, v27
	v_pk_fma_f32 v[136:137], v[16:17], v[136:137], v[128:129] neg_lo:[1,0,0] neg_hi:[1,0,0]
	v_pk_mul_f32 v[144:145], v[72:73], v[144:145]
	v_pk_fma_f32 v[54:55], v[16:17], v[56:57], v[54:55] neg_lo:[1,0,0] neg_hi:[1,0,0]
	v_add_f32_e32 v27, 1.0, v27
	v_rcp_f32_e32 v72, v27
	v_mul_f32_e32 v27, 0xbfb8aa3b, v71
	v_exp_f32_e32 v27, v27
	v_pk_mul_f32 v[128:129], v[136:137], v[136:137]
	v_pk_mul_f32 v[56:57], v[54:55], v[54:55]
	v_lshlrev_b32_e32 v150, 16, v151
	v_add_f32_e32 v27, 1.0, v27
	v_rcp_f32_e32 v73, v27
	v_add_f32_e32 v27, v128, v129
	v_add_f32_e32 v128, v56, v57
	v_add_f32_e32 v27, v128, v27
	v_add_f32_e32 v27, v27, v58
	v_add_f32_e32 v27, v27, v59
	v_add_f32_e32 v27, v27, v62
	v_add_f32_e32 v27, v27, v63
	v_add_f32_e32 v27, v27, v66
	v_add_f32_e32 v27, v27, v67
	ds_bpermute_b32 v128, v25, v27
	v_pk_mul_f32 v[70:71], v[72:73], v[70:71]
	v_pk_mul_f32 v[64:65], v[64:65], v[74:75]
	v_and_b32_e32 v151, 0xffff0000, v151
	v_pk_mul_f32 v[68:69], v[68:69], v[76:77]
	s_waitcnt lgkmcnt(0)
	v_add_f32_e32 v27, v27, v128
	ds_bpermute_b32 v128, v24, v27
	s_waitcnt lgkmcnt(0)
	v_add_f32_e32 v27, v27, v128
	ds_bpermute_b32 v128, v23, v27
	s_waitcnt lgkmcnt(0)
	v_add_f32_e32 v27, v27, v128
	ds_bpermute_b32 v128, v22, v27
	s_waitcnt lgkmcnt(0)
	v_add_f32_e32 v27, v27, v128
	v_fmamk_f32 v27, v27, 0x3b800000, v206
	v_cmp_gt_f32_e32 vcc, s5, v27
	v_mul_f32_e32 v128, 0x4b800000, v27
	s_nop 0
	v_cndmask_b32_e32 v27, v27, v128, vcc
	v_rsq_f32_e32 v27, v27
	s_nop 0
	v_mul_f32_e32 v128, 0x45800000, v27
	v_cndmask_b32_e32 v27, v27, v128, vcc
	v_mul_f32_e32 v56, v26, v27
	v_pk_mul_f32 v[128:129], v[54:55], v[56:57] op_sel_hi:[1,0]
	v_pk_mul_f32 v[136:137], v[136:137], v[56:57] op_sel_hi:[1,0]
	v_pk_mul_f32 v[128:129], v[0:1], v[128:129]
	v_pk_mul_f32 v[136:137], v[2:3], v[136:137]
	v_pk_mul_f32 v[128:129], v[70:71], v[128:129]
	v_pk_mul_f32 v[136:137], v[144:145], v[136:137]
	v_cvt_pk_bf16_f32 v128, v128, v129
	v_cvt_pk_bf16_f32 v129, v136, v137
	v_pk_mul_f32 v[130:131], v[130:131], v[56:57] op_sel_hi:[1,0]
	v_pk_mul_f32 v[136:137], v[138:139], v[56:57] op_sel_hi:[1,0]
	v_mul_f32_e32 v27, 0xbfb8aa3b, v150
	v_pk_mul_f32 v[130:131], v[4:5], v[130:131]
	v_pk_mul_f32 v[136:137], v[6:7], v[136:137]
	v_exp_f32_e32 v27, v27
	v_pk_mul_f32 v[130:131], v[60:61], v[130:131]
	v_pk_mul_f32 v[136:137], v[146:147], v[136:137]
	v_cvt_pk_bf16_f32 v130, v130, v131
	v_cvt_pk_bf16_f32 v131, v136, v137
	v_pk_mul_f32 v[132:133], v[132:133], v[56:57] op_sel_hi:[1,0]
	v_pk_mul_f32 v[136:137], v[140:141], v[56:57] op_sel_hi:[1,0]
	v_pk_mul_f32 v[132:133], v[8:9], v[132:133]
	v_pk_mul_f32 v[136:137], v[10:11], v[136:137]
	v_pk_mul_f32 v[132:133], v[64:65], v[132:133]
	v_pk_mul_f32 v[136:137], v[148:149], v[136:137]
	v_add_f32_e32 v27, 1.0, v27
	v_cvt_pk_bf16_f32 v132, v132, v133
	v_cvt_pk_bf16_f32 v133, v136, v137
	v_rcp_f32_e32 v136, v27
	v_mul_f32_e32 v27, 0xbfb8aa3b, v151
	v_exp_f32_e32 v27, v27
	v_pk_mul_f32 v[134:135], v[134:135], v[56:57] op_sel_hi:[1,0]
	v_pk_mul_f32 v[138:139], v[142:143], v[56:57] op_sel_hi:[1,0]
	v_pk_mul_f32 v[134:135], v[12:13], v[134:135]
	v_add_f32_e32 v27, 1.0, v27
	v_rcp_f32_e32 v137, v27
	v_pk_mul_f32 v[138:139], v[14:15], v[138:139]
	v_pk_mul_f32 v[134:135], v[68:69], v[134:135]
	v_pk_mul_f32 v[136:137], v[136:137], v[150:151]
	s_nop 0
	v_pk_mul_f32 v[136:137], v[136:137], v[138:139]
	v_cvt_pk_bf16_f32 v134, v134, v135
	v_cvt_pk_bf16_f32 v135, v136, v137
	v_add_co_u32_e32 v136, vcc, 0x11701000, v152
	s_nop 1
	v_addc_co_u32_e32 v137, vcc, 0, v153, vcc
	global_store_dwordx4 v[136:137], v[128:131], off offset:2048
	global_store_dwordx4 v[136:137], v[132:135], off offset:2064
	s_cbranch_scc1 .LBB0_657
	s_waitcnt vmcnt(0)
	s_mov_b32 s96, 0x800000
	s_branch .LBB0_486
